# P2: first-needed gate-stage inputs (two bias quads, first gain) requested at the unit head instead of after the MFMA stage
# baseline (speedup 1.0000x reference)
; #define LAS __attribute__((address_space(3)))
; __device__ __forceinline__ s16x4 vtr(const LAS unsigned char* p) { return __builtin_bit_cast(s16x4, __builtin_amdgcn_ds_read_tr16_b64_v4i16((LAS s16x4*)p)); }
; __device__ __forceinline__ int crow(int r, int hi) { return (r & 3) + 8 * (r >> 2) + 4 * hi; }
; #define lane lane_id()
; __device__ __forceinline__ void mix_unit(LAS unsigned char* lds, const int wid, int n, int g, const bf16_t* __restrict__ UZ, const bf16_t* __restrict__ V, const float* __restrict__ vss, ...
;     ...
;     {
;         const LAS unsigned char* vimg = lds + 32768 + (wid >> 2) * 32768;
;         const unsigned cblk = wid & 3, qa = (lane & 15) >> 2, blk = (lane >> 4) & 1, pp = lane & 3;
; #pragma unroll
;         for (int ks = 0; ks < 8; ++ks) {
;             const s16x4 lo = vtr(vimg + off_b(16 * ks + 8 * hi + qa, 4 * cblk + 2 * blk + (pp >> 1)) + 8 * (pp & 1));
;             const s16x4 hh = vtr(vimg + off_b(16 * ks + 8 * hi + 4 + qa, 4 * cblk + 2 * blk + (pp >> 1)) + 8 * (pp & 1));
;             const bf16x8 vf = (bf16x8){lo[0], lo[1], lo[2], lo[3], hh[0], hh[1], hh[2], hh[3]};
; #pragma unroll
;             for (int i = 0; i < 4; ++i) if (ks <= 2 * i + 1) {
;                 const bf16x8 af = *(const LAS bf16x8*)(lds + off_b(32 * i + r32, 2 * ks + hi));
;                 acc[i] = __builtin_amdgcn_mfma_f32_32x32x16_bf16(af, vf, acc[i], 0, 0, 0);
;             }
;         }
;     }
;     __syncthreads();
;     {
;         LAS float* mx = (LAS float*)lds;
;         const int c = 128 * (wid >> 2) + 32 * (wid & 3) + r32;
; #pragma unroll
;         for (int i = 0; i < 4; ++i)
; #pragma unroll
;             for (int r = 0; r < 16; ++r) mx[(32 * i + crow(r, hi)) * 256 + c] = acc[i][r];
;     }
;     __syncthreads();
.Lp2_mfma:
	ds_read_b64_tr_b16 v[0:1], v218 offset:32768
	ds_read_b64_tr_b16 v[2:3], v219 offset:33792
	ds_read_b128 v[4:7], v220
	s_waitcnt lgkmcnt(0)
	v_mfma_f32_32x32x16_bf16 v[48:63], v[4:7], v[0:3], 0
	ds_read_b128 v[4:7], v220 offset:8192
	s_lshl_b32 s72, s97, 8
	s_lshl_b32 s82, s72, 2
	s_mov_b32 s83, s77
	s_waitcnt lgkmcnt(0)
	v_mfma_f32_32x32x16_bf16 v[32:47], v[4:7], v[0:3], 0
	ds_read_b128 v[4:7], v220 offset:16384
	s_waitcnt lgkmcnt(0)
	v_mfma_f32_32x32x16_bf16 v[16:31], v[4:7], v[0:3], 0
	ds_read_b128 v[4:7], v220 offset:24576
	ds_read_b64_tr_b16 v[236:237], v218 offset:36864
	ds_read_b64_tr_b16 v[238:239], v219 offset:37888
	ds_read_b128 v[240:243], v221
	s_waitcnt lgkmcnt(0)
	v_mfma_f32_32x32x16_bf16 v[48:63], v[240:243], v[236:239], v[48:63]
	ds_read_b128 v[240:243], v221 offset:8192
	s_waitcnt lgkmcnt(0)
	v_mfma_f32_32x32x16_bf16 v[32:47], v[240:243], v[236:239], v[32:47]
	ds_read_b128 v[240:243], v221 offset:16384
	s_waitcnt lgkmcnt(0)
	v_mfma_f32_32x32x16_bf16 v[16:31], v[240:243], v[236:239], v[16:31]
	ds_read_b128 v[240:243], v221 offset:24576
	v_mfma_f32_32x32x16_bf16 v[0:15], v[4:7], v[0:3], 0
	s_waitcnt lgkmcnt(0)
	v_mfma_f32_32x32x16_bf16 v[0:15], v[240:243], v[236:239], v[0:15]
	ds_read_b64_tr_b16 v[236:237], v218 offset:40960
	ds_read_b64_tr_b16 v[238:239], v219 offset:41984
	ds_read_b128 v[240:243], v222 offset:8192
	s_waitcnt lgkmcnt(0)
	v_mfma_f32_32x32x16_bf16 v[32:47], v[240:243], v[236:239], v[32:47]
	ds_read_b128 v[240:243], v222 offset:16384
	s_waitcnt lgkmcnt(0)
	v_mfma_f32_32x32x16_bf16 v[16:31], v[240:243], v[236:239], v[16:31]
	ds_read_b128 v[240:243], v222 offset:24576
	s_waitcnt lgkmcnt(0)
	v_mfma_f32_32x32x16_bf16 v[0:15], v[240:243], v[236:239], v[0:15]
	ds_read_b64_tr_b16 v[236:237], v218 offset:45056
	ds_read_b64_tr_b16 v[238:239], v219 offset:46080
	ds_read_b128 v[240:243], v223 offset:8192
	s_waitcnt lgkmcnt(0)
	v_mfma_f32_32x32x16_bf16 v[32:47], v[240:243], v[236:239], v[32:47]
	ds_read_b128 v[240:243], v223 offset:16384
	s_waitcnt lgkmcnt(0)
	v_mfma_f32_32x32x16_bf16 v[16:31], v[240:243], v[236:239], v[16:31]
	ds_read_b128 v[240:243], v223 offset:24576
	s_waitcnt lgkmcnt(0)
	v_mfma_f32_32x32x16_bf16 v[0:15], v[240:243], v[236:239], v[0:15]
	ds_read_b64_tr_b16 v[236:237], v218 offset:49152
	ds_read_b64_tr_b16 v[238:239], v219 offset:50176
	ds_read_b128 v[240:243], v224 offset:16384
	s_waitcnt lgkmcnt(0)
	v_mfma_f32_32x32x16_bf16 v[16:31], v[240:243], v[236:239], v[16:31]
	ds_read_b128 v[240:243], v224 offset:24576
	s_waitcnt lgkmcnt(0)
	v_mfma_f32_32x32x16_bf16 v[0:15], v[240:243], v[236:239], v[0:15]
	ds_read_b64_tr_b16 v[236:237], v218 offset:53248
	ds_read_b64_tr_b16 v[238:239], v219 offset:54272
	ds_read_b128 v[240:243], v225 offset:16384
	s_waitcnt lgkmcnt(0)
	v_mfma_f32_32x32x16_bf16 v[16:31], v[240:243], v[236:239], v[16:31]
	ds_read_b128 v[240:243], v225 offset:24576
	s_waitcnt lgkmcnt(0)
	v_mfma_f32_32x32x16_bf16 v[0:15], v[240:243], v[236:239], v[0:15]
	ds_read_b64_tr_b16 v[236:237], v218 offset:57344
	ds_read_b64_tr_b16 v[238:239], v219 offset:58368
	ds_read_b128 v[240:243], v226 offset:24576
	s_waitcnt lgkmcnt(0)
	v_mfma_f32_32x32x16_bf16 v[0:15], v[240:243], v[236:239], v[0:15]
	ds_read_b64_tr_b16 v[236:237], v218 offset:61440
	ds_read_b64_tr_b16 v[238:239], v219 offset:62464
	ds_read_b128 v[240:243], v227 offset:24576
	s_waitcnt lgkmcnt(0)
	s_barrier
	v_mfma_f32_32x32x16_bf16 v[0:15], v[240:243], v[236:239], v[0:15]
	ds_write2st64_b32 v171, v48, v49 offset1:4
	ds_write2st64_b32 v171, v50, v51 offset0:8 offset1:12
	ds_write2st64_b32 v171, v52, v53 offset0:32 offset1:36
	ds_write2st64_b32 v171, v54, v55 offset0:40 offset1:44
	ds_write2st64_b32 v171, v56, v57 offset0:64 offset1:68
	ds_write2st64_b32 v171, v58, v59 offset0:72 offset1:76
	ds_write2st64_b32 v171, v60, v61 offset0:96 offset1:100
	ds_write2st64_b32 v171, v62, v63 offset0:104 offset1:108
	ds_write2st64_b32 v171, v32, v33 offset0:128 offset1:132
	ds_write2st64_b32 v171, v34, v35 offset0:136 offset1:140
	ds_write2st64_b32 v171, v36, v37 offset0:160 offset1:164
	ds_write2st64_b32 v171, v38, v39 offset0:168 offset1:172
	ds_write2st64_b32 v171, v40, v41 offset0:192 offset1:196
	ds_write2st64_b32 v171, v42, v43 offset0:200 offset1:204
	ds_write2st64_b32 v171, v44, v45 offset0:224 offset1:228
	ds_write2st64_b32 v171, v46, v47 offset0:232 offset1:236
	ds_write_b32 v172, v16
	ds_write_b32 v173, v17
	ds_write_b32 v174, v18
	ds_write_b32 v175, v19
	ds_write_b32 v176, v20
	ds_write_b32 v177, v21
	ds_write_b32 v178, v22
	ds_write_b32 v179, v23
	ds_write_b32 v180, v24
	ds_write_b32 v181, v25
	ds_write_b32 v182, v26
	ds_write_b32 v183, v27
	ds_write_b32 v184, v28
	ds_write_b32 v185, v29
	ds_write_b32 v186, v30
	ds_write_b32 v187, v31
	ds_write_b32 v188, v0
	ds_write_b32 v189, v1
	ds_write_b32 v190, v2
	ds_write_b32 v191, v3
	ds_write_b32 v192, v4
	ds_write_b32 v193, v5
	ds_write_b32 v194, v6
	ds_write_b32 v196, v7
	ds_write_b32 v197, v8
	ds_write_b32 v198, v9
	ds_write_b32 v199, v10
	ds_write_b32 v200, v11
	ds_write_b32 v201, v12
	ds_write_b32 v202, v13
	ds_write_b32 v203, v14
	ds_write_b32 v204, v15
	v_lshl_add_u64 v[4:5], v[142:143], 0, s[82:83]
	s_waitcnt lgkmcnt(0)
	s_barrier
; #define LAS __attribute__((address_space(3)))
; __device__ __forceinline__ unsigned pk_bf16(float lo, float hi) { return pg8::cvt_pk_bf16(lo, hi); }
; __device__ __forceinline__ float bf_lo(unsigned w) { return __uint_as_float(w << 16); }
; __device__ __forceinline__ float bf_hi(unsigned w) { return __uint_as_float(w & 0xffff0000u); }
; #define tid tid_of(wave)
; __device__ __forceinline__ void mix_unit(LAS unsigned char* lds, const int wid, int n, int g, const bf16_t* __restrict__ UZ, const bf16_t* __restrict__ V, const float* __restrict__ vss, ...
;     ...
;     {
;         const f32x4 g0 = *(const f32x4*)(vg + g * GDIM + cc * 8), g1 = *(const f32x4*)(vg + g * GDIM + cc * 8 + 4);
;         float bb[8];
; #pragma unroll
;         for (int i = 0; i < 8; ++i) bb[i] = b_s[g * CHUNK + (tid >> 5) + 16 * i];
; #pragma unroll
;         for (int i = 0; i < 8; ++i) { const int t = (tid >> 5) + 16 * i;
;             const f32x4 m0 = *(const LAS f32x4*)(lds + (t * 256 + cc * 8) * 4), m1 = *(const LAS f32x4*)(lds + (t * 256 + cc * 8 + 4) * 4);
;             float y[8];
;             y[0] = bf_lo(uu[i].x) * (m0[0] * g0[0] + bb[i]); y[1] = bf_hi(uu[i].x) * (m0[1] * g0[1] + bb[i]);
;             y[2] = bf_lo(uu[i].y) * (m0[2] * g0[2] + bb[i]); y[3] = bf_hi(uu[i].y) * (m0[3] * g0[3] + bb[i]);
;             y[4] = bf_lo(uu[i].z) * (m1[0] * g1[0] + bb[i]); y[5] = bf_hi(uu[i].z) * (m1[1] * g1[1] + bb[i]);
;             y[6] = bf_lo(uu[i].w) * (m1[2] * g1[2] + bb[i]); y[7] = bf_hi(uu[i].w) * (m1[3] * g1[3] + bb[i]);
;             u32x4 w; w.x = pk_bf16(y[0], y[1]); w.y = pk_bf16(y[2], y[3]); w.z = pk_bf16(y[4], y[5]); w.w = pk_bf16(y[6], y[7]);
;             *(u32x4*)(Y + (row0 + t) * GW + g * GDIM + cc * 8) = w; }
	s_waitcnt vmcnt(0)
	v_mov_b32_e32 v0, v244
	v_mov_b32_e32 v1, v245
	v_mov_b32_e32 v2, v246
	v_mov_b32_e32 v3, v247
	v_mov_b32_e32 v4, v166
	v_mov_b32_e32 v5, v167
	v_mov_b32_e32 v6, v168
	v_mov_b32_e32 v7, v169
	v_mov_b32_e32 v18, v165
	v_add_u32_e32 v8, s76, v96
	v_readlane_b32 s80, v248, 6
	v_ashrrev_i32_e32 v9, 31, v8
	v_readlane_b32 s90, v248, 16
	v_readlane_b32 s91, v248, 17
	v_lshlrev_b32_e32 v26, 16, v92
	s_lshl_b32 s76, s72, 1
	v_lshl_add_u64 v[8:9], v[8:9], 2, s[90:91]
	global_load_dword v19, v[8:9], off offset:64
	global_load_dword v20, v[8:9], off offset:128
	global_load_dword v21, v[8:9], off offset:192
	global_load_dword v22, v[8:9], off offset:256
	global_load_dword v23, v[8:9], off offset:320
	global_load_dword v24, v[8:9], off offset:384
	global_load_dword v25, v[8:9], off offset:448
	ds_read_b128 v[10:13], v228
	ds_read_b128 v[14:17], v228 offset:16
	v_lshl_add_u64 v[8:9], v[144:145], 0, s[76:77]
	v_readlane_b32 s88, v248, 14
	v_readlane_b32 s89, v248, 15
	v_readlane_b32 s88, v248, 35
	s_add_i32 s71, s71, s88
	v_readlane_b32 s89, v248, 36
	s_cmpk_lt_i32 s71, 0x400
	v_readlane_b32 s81, v248, 7
	v_readlane_b32 s82, v248, 8
	v_readlane_b32 s83, v248, 9
	v_readlane_b32 s84, v248, 10
	v_readlane_b32 s85, v248, 11
	v_readlane_b32 s86, v248, 12
	v_readlane_b32 s87, v248, 13
	v_readlane_b32 s92, v248, 18
	v_readlane_b32 s93, v248, 19
	v_readlane_b32 s94, v248, 20
	v_readlane_b32 s95, v248, 21
	s_waitcnt vmcnt(7) lgkmcnt(0)
	v_fma_f32 v14, v0, v14, v18
	v_fma_f32 v10, v4, v10, v18
	v_mul_f32_e32 v10, v10, v26
	v_and_b32_e32 v26, 0xffff0000, v92
	v_fma_f32 v11, v5, v11, v18
	v_mul_f32_e32 v11, v11, v26
	v_lshlrev_b32_e32 v26, 16, v93
	v_fma_f32 v12, v6, v12, v18
	v_mul_f32_e32 v12, v12, v26
	v_and_b32_e32 v26, 0xffff0000, v93
	v_fma_f32 v13, v7, v13, v18
	v_mul_f32_e32 v13, v13, v26
	v_lshlrev_b32_e32 v26, 16, v94
	v_mul_f32_e32 v14, v14, v26
	v_and_b32_e32 v26, 0xffff0000, v94
	v_fma_f32 v15, v1, v15, v18
	v_mul_f32_e32 v15, v15, v26
	v_lshlrev_b32_e32 v26, 16, v95
	v_fma_f32 v16, v2, v16, v18
	v_mul_f32_e32 v16, v16, v26
	v_and_b32_e32 v26, 0xffff0000, v95
	v_fmac_f32_e32 v18, v3, v17
	v_cvt_pk_bf16_f32 v10, v10, v11
	v_cvt_pk_bf16_f32 v11, v12, v13
	v_cvt_pk_bf16_f32 v12, v14, v15
	v_lshl_add_u64 v[14:15], v[8:9], 0, v[162:163]
	v_mul_f32_e32 v17, v18, v26
	v_cvt_pk_bf16_f32 v13, v16, v17
	global_store_dwordx4 v[14:15], v[10:13], off sc1
	ds_read_b128 v[10:13], v229
	ds_read_b128 v[14:17], v229 offset:16
	v_lshlrev_b32_e32 v18, 16, v88
	s_waitcnt vmcnt(7) lgkmcnt(1)
	v_fma_f32 v10, v4, v10, v19
	v_mul_f32_e32 v10, v10, v18
	v_and_b32_e32 v18, 0xffff0000, v88
	v_fma_f32 v11, v5, v11, v19
	v_mul_f32_e32 v11, v11, v18
	v_lshlrev_b32_e32 v18, 16, v89
	v_fma_f32 v12, v6, v12, v19
	v_mul_f32_e32 v12, v12, v18
	v_and_b32_e32 v18, 0xffff0000, v89
	v_fma_f32 v13, v7, v13, v19
	v_mul_f32_e32 v13, v13, v18
	v_lshlrev_b32_e32 v18, 16, v90
	s_waitcnt lgkmcnt(0)
	v_fma_f32 v14, v0, v14, v19
	v_mul_f32_e32 v14, v14, v18
	v_and_b32_e32 v18, 0xffff0000, v90
	v_fma_f32 v15, v1, v15, v19
	v_mul_f32_e32 v15, v15, v18
	v_lshlrev_b32_e32 v18, 16, v91
	v_fma_f32 v16, v2, v16, v19
	v_mul_f32_e32 v16, v16, v18
	v_and_b32_e32 v18, 0xffff0000, v91
	v_fmac_f32_e32 v19, v3, v17
	v_cvt_pk_bf16_f32 v10, v10, v11
	v_cvt_pk_bf16_f32 v11, v12, v13
	v_cvt_pk_bf16_f32 v12, v14, v15
	v_lshl_add_u64 v[14:15], v[8:9], 0, v[160:161]
	v_mul_f32_e32 v17, v19, v18
	v_cvt_pk_bf16_f32 v13, v16, v17
	global_store_dwordx4 v[14:15], v[10:13], off sc1
	ds_read_b128 v[10:13], v230
	ds_read_b128 v[14:17], v230 offset:16
	v_lshlrev_b32_e32 v18, 16, v84
	s_waitcnt vmcnt(7) lgkmcnt(1)
	v_fma_f32 v10, v4, v10, v20
	v_mul_f32_e32 v10, v10, v18
	v_and_b32_e32 v18, 0xffff0000, v84
	v_fma_f32 v11, v5, v11, v20
	v_mul_f32_e32 v11, v11, v18
	v_lshlrev_b32_e32 v18, 16, v85
	v_fma_f32 v12, v6, v12, v20
	v_mul_f32_e32 v12, v12, v18
	v_and_b32_e32 v18, 0xffff0000, v85
	v_fma_f32 v13, v7, v13, v20
	v_mul_f32_e32 v13, v13, v18
	v_lshlrev_b32_e32 v18, 16, v86
	s_waitcnt lgkmcnt(0)
	v_fma_f32 v14, v0, v14, v20
	v_mul_f32_e32 v14, v14, v18
	v_and_b32_e32 v18, 0xffff0000, v86
	v_fma_f32 v15, v1, v15, v20
	v_mul_f32_e32 v15, v15, v18
	v_lshlrev_b32_e32 v18, 16, v87
	v_fma_f32 v16, v2, v16, v20
	v_mul_f32_e32 v16, v16, v18
	v_and_b32_e32 v18, 0xffff0000, v87
	v_fmac_f32_e32 v20, v3, v17
	v_cvt_pk_bf16_f32 v10, v10, v11
	v_cvt_pk_bf16_f32 v11, v12, v13
	v_cvt_pk_bf16_f32 v12, v14, v15
	v_lshl_add_u64 v[14:15], v[8:9], 0, v[158:159]
	v_mul_f32_e32 v17, v20, v18
	v_cvt_pk_bf16_f32 v13, v16, v17
	global_store_dwordx4 v[14:15], v[10:13], off sc1
	ds_read_b128 v[10:13], v231
	ds_read_b128 v[14:17], v231 offset:16
	v_lshlrev_b32_e32 v18, 16, v80
	s_waitcnt vmcnt(7) lgkmcnt(1)
	v_fma_f32 v10, v4, v10, v21
	v_mul_f32_e32 v10, v10, v18
	v_and_b32_e32 v18, 0xffff0000, v80
	v_fma_f32 v11, v5, v11, v21
	v_mul_f32_e32 v11, v11, v18
	v_lshlrev_b32_e32 v18, 16, v81
	v_fma_f32 v12, v6, v12, v21
	v_mul_f32_e32 v12, v12, v18
	v_and_b32_e32 v18, 0xffff0000, v81
	v_fma_f32 v13, v7, v13, v21
	v_mul_f32_e32 v13, v13, v18
	v_lshlrev_b32_e32 v18, 16, v82
	s_waitcnt lgkmcnt(0)
	v_fma_f32 v14, v0, v14, v21
	v_mul_f32_e32 v14, v14, v18
	v_and_b32_e32 v18, 0xffff0000, v82
	v_fma_f32 v15, v1, v15, v21
	v_mul_f32_e32 v15, v15, v18
	v_lshlrev_b32_e32 v18, 16, v83
	v_fma_f32 v16, v2, v16, v21
	v_mul_f32_e32 v16, v16, v18
	v_and_b32_e32 v18, 0xffff0000, v83
	v_fmac_f32_e32 v21, v3, v17
	v_cvt_pk_bf16_f32 v10, v10, v11
	v_cvt_pk_bf16_f32 v11, v12, v13
	v_cvt_pk_bf16_f32 v12, v14, v15
	v_lshl_add_u64 v[14:15], v[8:9], 0, v[156:157]
	v_mul_f32_e32 v17, v21, v18
	v_cvt_pk_bf16_f32 v13, v16, v17
	global_store_dwordx4 v[14:15], v[10:13], off sc1
	ds_read_b128 v[10:13], v232
	ds_read_b128 v[14:17], v232 offset:16
	v_lshlrev_b32_e32 v18, 16, v76
	s_waitcnt vmcnt(7) lgkmcnt(1)
; #define LAS __attribute__((address_space(3)))
; __device__ __forceinline__ unsigned pk_bf16(float lo, float hi) { return pg8::cvt_pk_bf16(lo, hi); }
; __device__ __forceinline__ float bf_lo(unsigned w) { return __uint_as_float(w << 16); }
; __device__ __forceinline__ float bf_hi(unsigned w) { return __uint_as_float(w & 0xffff0000u); }
; #define tid tid_of(wave)
; __device__ __forceinline__ void mix_unit(LAS unsigned char* lds, const int wid, int n, int g, const bf16_t* __restrict__ UZ, const bf16_t* __restrict__ V, const float* __restrict__ vss, ...
;     ...
;         for (int i = 0; i < 8; ++i) { const int t = (tid >> 5) + 16 * i;
;             const f32x4 m0 = *(const LAS f32x4*)(lds + (t * 256 + cc * 8) * 4), m1 = *(const LAS f32x4*)(lds + (t * 256 + cc * 8 + 4) * 4);
;             float y[8];
;             y[0] = bf_lo(uu[i].x) * (m0[0] * g0[0] + bb[i]); y[1] = bf_hi(uu[i].x) * (m0[1] * g0[1] + bb[i]);
;             y[2] = bf_lo(uu[i].y) * (m0[2] * g0[2] + bb[i]); y[3] = bf_hi(uu[i].y) * (m0[3] * g0[3] + bb[i]);
;             y[4] = bf_lo(uu[i].z) * (m1[0] * g1[0] + bb[i]); y[5] = bf_hi(uu[i].z) * (m1[1] * g1[1] + bb[i]);
;             y[6] = bf_lo(uu[i].w) * (m1[2] * g1[2] + bb[i]); y[7] = bf_hi(uu[i].w) * (m1[3] * g1[3] + bb[i]);
;             u32x4 w; w.x = pk_bf16(y[0], y[1]); w.y = pk_bf16(y[2], y[3]); w.z = pk_bf16(y[4], y[5]); w.w = pk_bf16(y[6], y[7]);
;             *(u32x4*)(Y + (row0 + t) * GW + g * GDIM + cc * 8) = w; }
;     }
;     __syncthreads();
	v_fma_f32 v10, v4, v10, v22
	v_mul_f32_e32 v10, v10, v18
	v_and_b32_e32 v18, 0xffff0000, v76
	v_fma_f32 v11, v5, v11, v22
	v_mul_f32_e32 v11, v11, v18
	v_lshlrev_b32_e32 v18, 16, v77
	v_fma_f32 v12, v6, v12, v22
	v_mul_f32_e32 v12, v12, v18
	v_and_b32_e32 v18, 0xffff0000, v77
	v_fma_f32 v13, v7, v13, v22
	v_mul_f32_e32 v13, v13, v18
	v_lshlrev_b32_e32 v18, 16, v78
	s_waitcnt lgkmcnt(0)
	v_fma_f32 v14, v0, v14, v22
	v_mul_f32_e32 v14, v14, v18
	v_and_b32_e32 v18, 0xffff0000, v78
	v_fma_f32 v15, v1, v15, v22
	v_mul_f32_e32 v15, v15, v18
	v_lshlrev_b32_e32 v18, 16, v79
	v_fma_f32 v16, v2, v16, v22
	v_mul_f32_e32 v16, v16, v18
	v_and_b32_e32 v18, 0xffff0000, v79
	v_fmac_f32_e32 v22, v3, v17
	v_cvt_pk_bf16_f32 v10, v10, v11
	v_cvt_pk_bf16_f32 v11, v12, v13
	v_cvt_pk_bf16_f32 v12, v14, v15
	v_lshl_add_u64 v[14:15], v[8:9], 0, v[154:155]
	v_mul_f32_e32 v17, v22, v18
	v_cvt_pk_bf16_f32 v13, v16, v17
	global_store_dwordx4 v[14:15], v[10:13], off sc1
	ds_read_b128 v[10:13], v233
	ds_read_b128 v[14:17], v233 offset:16
	v_lshlrev_b32_e32 v18, 16, v72
	s_waitcnt vmcnt(7) lgkmcnt(1)
	v_fma_f32 v10, v4, v10, v23
	v_mul_f32_e32 v10, v10, v18
	v_and_b32_e32 v18, 0xffff0000, v72
	v_fma_f32 v11, v5, v11, v23
	v_mul_f32_e32 v11, v11, v18
	v_lshlrev_b32_e32 v18, 16, v73
	v_fma_f32 v12, v6, v12, v23
	v_mul_f32_e32 v12, v12, v18
	v_and_b32_e32 v18, 0xffff0000, v73
	v_fma_f32 v13, v7, v13, v23
	v_mul_f32_e32 v13, v13, v18
	v_lshlrev_b32_e32 v18, 16, v74
	s_waitcnt lgkmcnt(0)
	v_fma_f32 v14, v0, v14, v23
	v_mul_f32_e32 v14, v14, v18
	v_and_b32_e32 v18, 0xffff0000, v74
	v_fma_f32 v15, v1, v15, v23
	v_mul_f32_e32 v15, v15, v18
	v_lshlrev_b32_e32 v18, 16, v75
	v_fma_f32 v16, v2, v16, v23
	v_mul_f32_e32 v16, v16, v18
	v_and_b32_e32 v18, 0xffff0000, v75
	v_fmac_f32_e32 v23, v3, v17
	v_cvt_pk_bf16_f32 v10, v10, v11
	v_cvt_pk_bf16_f32 v11, v12, v13
	v_cvt_pk_bf16_f32 v12, v14, v15
	v_lshl_add_u64 v[14:15], v[8:9], 0, v[150:151]
	v_mul_f32_e32 v17, v23, v18
	v_cvt_pk_bf16_f32 v13, v16, v17
	global_store_dwordx4 v[14:15], v[10:13], off sc1
	ds_read_b128 v[10:13], v234
	ds_read_b128 v[14:17], v234 offset:16
	v_lshlrev_b32_e32 v18, 16, v68
	s_waitcnt vmcnt(7) lgkmcnt(1)
	v_fma_f32 v10, v4, v10, v24
	v_mul_f32_e32 v10, v10, v18
	v_and_b32_e32 v18, 0xffff0000, v68
	v_fma_f32 v11, v5, v11, v24
	v_mul_f32_e32 v11, v11, v18
	v_lshlrev_b32_e32 v18, 16, v69
	v_fma_f32 v12, v6, v12, v24
	v_mul_f32_e32 v12, v12, v18
	v_and_b32_e32 v18, 0xffff0000, v69
	v_fma_f32 v13, v7, v13, v24
	v_mul_f32_e32 v13, v13, v18
	v_lshlrev_b32_e32 v18, 16, v70
	s_waitcnt lgkmcnt(0)
	v_fma_f32 v14, v0, v14, v24
	v_mul_f32_e32 v14, v14, v18
	v_and_b32_e32 v18, 0xffff0000, v70
	v_fma_f32 v15, v1, v15, v24
	v_mul_f32_e32 v15, v15, v18
	v_lshlrev_b32_e32 v18, 16, v71
	v_fma_f32 v16, v2, v16, v24
	v_mul_f32_e32 v16, v16, v18
	v_and_b32_e32 v18, 0xffff0000, v71
	v_fmac_f32_e32 v24, v3, v17
	v_cvt_pk_bf16_f32 v10, v10, v11
	v_cvt_pk_bf16_f32 v11, v12, v13
	v_cvt_pk_bf16_f32 v12, v14, v15
	v_lshl_add_u64 v[14:15], v[8:9], 0, v[148:149]
	v_mul_f32_e32 v17, v24, v18
	v_cvt_pk_bf16_f32 v13, v16, v17
	global_store_dwordx4 v[14:15], v[10:13], off sc1
	ds_read_b128 v[10:13], v235
	ds_read_b128 v[14:17], v235 offset:16
	v_lshlrev_b32_e32 v18, 16, v64
	s_waitcnt vmcnt(7) lgkmcnt(1)
	v_fma_f32 v4, v4, v10, v25
	v_and_b32_e32 v10, 0xffff0000, v64
	v_fma_f32 v5, v5, v11, v25
	v_mul_f32_e32 v5, v5, v10
	v_lshlrev_b32_e32 v10, 16, v65
	v_fma_f32 v6, v6, v12, v25
	v_mul_f32_e32 v6, v6, v10
	v_and_b32_e32 v10, 0xffff0000, v65
	v_fma_f32 v7, v7, v13, v25
	v_mul_f32_e32 v7, v7, v10
	v_lshlrev_b32_e32 v10, 16, v66
	s_waitcnt lgkmcnt(0)
	v_fma_f32 v0, v0, v14, v25
	v_mul_f32_e32 v10, v0, v10
	v_and_b32_e32 v0, 0xffff0000, v66
	v_fma_f32 v1, v1, v15, v25
	v_mul_f32_e32 v11, v1, v0
	v_lshlrev_b32_e32 v0, 16, v67
	v_fma_f32 v1, v2, v16, v25
	v_mul_f32_e32 v4, v4, v18
	v_mul_f32_e32 v12, v1, v0
	v_and_b32_e32 v0, 0xffff0000, v67
	v_fmac_f32_e32 v25, v3, v17
	v_mul_f32_e32 v3, v25, v0
	v_cvt_pk_bf16_f32 v0, v4, v5
	v_lshl_add_u64 v[4:5], v[8:9], 0, v[146:147]
	v_cvt_pk_bf16_f32 v1, v6, v7
	v_cvt_pk_bf16_f32 v2, v10, v11
	v_cvt_pk_bf16_f32 v3, v12, v3
	global_store_dwordx4 v[4:5], v[0:3], off sc1
	s_barrier
	s_cbranch_scc0 .LBB0_331
; __device__ __forceinline__ int tid_of(int wave) { return wave * 64 + lane_id(); }
; #define LAS __attribute__((address_space(3)))
; #define tid tid_of(wave)
; #define lane lane_id()
; __device__ __forceinline__ void mix_unit(LAS unsigned char* lds, const int wid, int n, int g, const bf16_t* __restrict__ UZ, const bf16_t* __restrict__ V, const float* __restrict__ vss, ...
;     const int tid = tid_of(wid), lane = tid & 63, r32 = lane & 31, hi = lane >> 5;
;     const size_t row0 = (size_t)n * CHUNK;
;     LAS float* rstdL = (LAS float*)(lds + 98304);
;     const int cc = tid & 31;
;     u32x4 uu[8];
; #pragma unroll
;     for (int i = 0; i < 8; ++i) { const int t = (tid >> 5) + 16 * i; uu[i] = __builtin_nontemporal_load((const u32x4*)(UZ + (row0 + t) * GW + g * GDIM + cc * 8)); }
;     ...
;         const f32x4 g0 = *(const f32x4*)(vg + g * GDIM + cc * 8), g1 = *(const f32x4*)(vg + g * GDIM + cc * 8 + 4);
;     ...
;         for (int i = 0; i < 8; ++i) bb[i] = b_s[g * CHUNK + (tid >> 5) + 16 * i];
.LBB0_265:
	s_ashr_i32 s72, s71, 4
	s_ashr_i32 s73, s72, 31
	s_and_b32 s97, s71, 15
	s_lshl_b64 s[72:73], s[72:73], 7
	s_lshl_b32 s76, s97, 9
	s_waitcnt lgkmcnt(0)
	s_lshl_b32 s100, s97, 10
	s_mov_b32 s101, 0
	v_lshl_add_u64 v[236:237], v[142:143], 0, s[100:101]
	global_load_dwordx4 v[244:247], v[236:237], off offset:16
	global_load_dwordx4 v[166:169], v[236:237], off
	s_lshl_b32 s78, s97, 7
	v_readlane_b32 s98, v248, 16
	v_readlane_b32 s99, v248, 17
	v_add_u32_e32 v238, s78, v96
	v_ashrrev_i32_e32 v239, 31, v238
	v_lshl_add_u64 v[238:239], v[238:239], 2, s[98:99]
	global_load_dword v165, v[238:239], off
	v_lshl_add_u64 v[236:237], s[72:73], 0, v[96:97]
	v_lshlrev_b64 v[162:163], 13, v[236:237]
	v_lshl_add_u64 v[236:237], s[72:73], 0, v[100:101]
	v_lshlrev_b64 v[160:161], 13, v[236:237]
	v_lshl_add_u64 v[236:237], s[72:73], 0, v[102:103]
	v_lshlrev_b64 v[158:159], 13, v[236:237]
	v_lshl_add_u64 v[236:237], s[72:73], 0, v[104:105]
	v_lshlrev_b64 v[156:157], 13, v[236:237]
	v_lshl_add_u64 v[236:237], s[72:73], 0, v[106:107]
	v_lshlrev_b64 v[154:155], 13, v[236:237]
	v_lshl_add_u64 v[236:237], s[72:73], 0, v[108:109]
	v_lshlrev_b64 v[150:151], 13, v[236:237]
	v_lshl_add_u64 v[236:237], s[72:73], 0, v[110:111]
	v_lshlrev_b64 v[148:149], 13, v[236:237]
	v_lshl_add_u64 v[236:237], s[72:73], 0, v[112:113]
	v_lshlrev_b64 v[146:147], 13, v[236:237]
	v_lshl_add_u64 v[238:239], v[114:115], 0, s[76:77]
	v_lshl_add_u64 v[240:241], v[238:239], 0, v[162:163]
	global_load_dwordx4 v[0:3], v[240:241], off nt
	v_lshl_add_u64 v[236:237], s[72:73], 0, v[116:117]
	v_lshlrev_b64 v[236:237], 13, v[236:237]
	v_lshl_add_u64 v[240:241], v[238:239], 0, v[236:237]
	global_load_dwordx4 v[4:7], v[240:241], off nt
	v_lshl_add_u64 v[236:237], s[72:73], 0, v[118:119]
	v_lshlrev_b64 v[236:237], 13, v[236:237]
	v_lshl_add_u64 v[240:241], v[238:239], 0, v[236:237]
	global_load_dwordx4 v[8:11], v[240:241], off nt
	v_lshl_add_u64 v[236:237], s[72:73], 0, v[120:121]
	v_lshlrev_b64 v[236:237], 13, v[236:237]
	v_lshl_add_u64 v[240:241], v[238:239], 0, v[236:237]
	global_load_dwordx4 v[12:15], v[240:241], off nt
	v_lshl_add_u64 v[236:237], s[72:73], 0, v[122:123]
	v_lshlrev_b64 v[236:237], 13, v[236:237]
	v_lshl_add_u64 v[240:241], v[238:239], 0, v[236:237]
	global_load_dwordx4 v[16:19], v[240:241], off nt
	v_lshl_add_u64 v[236:237], s[72:73], 0, v[124:125]
	v_lshlrev_b64 v[236:237], 13, v[236:237]
	v_lshl_add_u64 v[240:241], v[238:239], 0, v[236:237]
	global_load_dwordx4 v[20:23], v[240:241], off nt
	v_lshl_add_u64 v[236:237], s[72:73], 0, v[126:127]
	v_lshlrev_b64 v[236:237], 13, v[236:237]
	v_lshl_add_u64 v[240:241], v[238:239], 0, v[236:237]
	global_load_dwordx4 v[24:27], v[240:241], off nt
	v_lshl_add_u64 v[236:237], s[72:73], 0, v[128:129]
	v_lshlrev_b64 v[236:237], 13, v[236:237]
	v_lshl_add_u64 v[240:241], v[238:239], 0, v[236:237]
	global_load_dwordx4 v[28:31], v[240:241], off nt
	s_and_saveexec_b64 s[82:83], vcc
	s_cbranch_execz .Lp2_a
	v_lshl_add_u64 v[242:243], s[72:73], 2, v[130:131]
	global_load_dword v242, v[242:243], off
